# FFN1-down K-loop: every wave touches one 64-lane group of A-operand lines 4-5 K-tiles ahead, each of the four column-tile workgroups of a row panel covering a different quarter, so the shared A stream
# speedup vs baseline: 1.0051x; 1.0051x over previous
; #define PG8_STAGE(bufoff, gbase, voff) do { _Pragma("unroll") for (int _i = 0; _i < 2; ++_i) \
;         __builtin_amdgcn_global_load_lds((const unsigned*)((const char*)(gbase) + (voff)[_i]), (PG8_LAS unsigned*)(lds + (bufoff) + ldsw + _i * 8192), 16, 0, 0); } while (0)
; #define PG8_WAIT_V(n) asm volatile("s_waitcnt vmcnt(" #n ")" ::: "memory")
; #define PG8_BAR __builtin_amdgcn_s_barrier()
; template <class Epi, class Sched, bool ALIGN_EPI = false, bool SP2 = false>
; __device__ __forceinline__ void gemm_phase(PG8_LAS unsigned char* lds, const Gemm g, const Sched& S, const Epi& E) {
;     ...
;     for (int i = 0; i < 2; ++i) { int R, C; stage_rc(tid * 16 + i * 8192, R, C); const int Rb = Epi::PERM ? ((R & ~31) + perm32(R & 31)) : R;
;         voffA[i] = (unsigned)(R * K + C) * 2u; voffB[i] = (unsigned)(Rb * K + C) * 2u; }
;     const size_t kstep = (size_t)(BK * 2);
;     const size_t hstep = (size_t)HALF * K * 2;
;     const size_t tstep = 2 * hstep;
;     const unsigned ldsw = (unsigned)wid * 1024u;
;     const int aoff = lds_byte(wr * 64 + fr, fq * 8), boff = lds_byte(wc * 32 + fr, fq * 8);
;     ...
;         PG8_STAGE(PG8_SB(0, 0), cB, voffB); PG8_STAGE(PG8_SB(0, 1), cB + hstep, voffB); PG8_STAGE(PG8_SA(0, 0), cA, voffA); PG8_STAGE(PG8_SA(0, 1), cA + hstep, voffA);
;         if (wr == 1) PG8_BAR;
;         PG8_WAIT_V(2); PG8_BAR;
;         PG8_STAGE(PG8_SB(1, 0), cB + kstep, voffB); PG8_STAGE(PG8_SA(1, 0), cA + kstep, voffA); PG8_STAGE(PG8_SB(1, 1), cB + hstep + kstep, voffB);
;         PG8_WAIT_V(6); PG8_BAR;
.LBB0_257:
	s_add_u32 s38, s38, 0xf8000000
	s_mov_b64 s[18:19], 0x80
	s_addc_u32 s39, s39, -1
	s_and_b32 s1, s1, 3
	s_add_i32 m0, s40, 0x18000
	v_lshl_add_u64 v[6:7], v[6:7], 0, s[18:19]
	s_lshl_b32 s4, s0, 13
	s_lshl_b32 s5, s1, 12
	s_waitcnt vmcnt(2)
	s_barrier
	global_load_lds_dwordx4 v[6:7], off
	v_lshl_add_u64 v[4:5], v[4:5], 0, s[18:19]
	s_add_i32 m0, s40, 0x1a000
	s_add_i32 s45, s40, 0x8000
	s_add_i32 s46, s40, 0xa000
	global_load_lds_dwordx4 v[4:5], off
	v_lshl_add_u64 v[2:3], v[2:3], 0, s[18:19]
	s_mov_b32 m0, s45
	s_add_u32 s2, s22, 0xb0080
	global_load_lds_dwordx4 v[2:3], off
	v_lshl_add_u64 v[0:1], v[0:1], 0, s[18:19]
	s_mov_b32 m0, s46
	s_addc_u32 s3, s23, 0
	global_load_lds_dwordx4 v[0:1], off
	s_add_i32 m0, s40, 0x1c000
	v_lshl_add_u64 v[0:1], s[2:3], 0, v[146:147]
	global_load_lds_dwordx4 v[0:1], off
	v_lshl_add_u64 v[0:1], s[2:3], 0, v[150:151]
	s_add_i32 m0, s40, 0x1e000
	v_lshlrev_b32_e32 v5, 6, v230
	global_load_lds_dwordx4 v[0:1], off
	v_bfe_u32 v0, v230, 4, 2
	v_and_b32_e32 v1, 15, v230
	v_lshl_or_b32 v168, s0, 6, v1
	v_lshlrev_b32_e32 v3, 4, v0
	s_movk_i32 s0, 0x3c0
	v_lshl_or_b32 v1, v1, 6, v3
	v_and_or_b32 v3, v5, s0, v3
	s_ashr_i32 s47, s11, 31
	s_ashr_i32 s48, s10, 31
	s_lshl_b32 s0, s1, 2
	v_lshlrev_b32_e32 v2, 3, v0
	s_add_u32 s0, s58, s0
	v_lshlrev_b32_e32 v4, 2, v230
	v_lshl_or_b32 v170, s1, 5, v2
	v_cmp_eq_u32_e64 s[2:3], 0, v0
	s_addc_u32 s1, s59, 0
	v_add_u16_e32 v0, v8, v9
	v_and_b32_e32 v4, 32, v4
	s_waitcnt vmcnt(6)
	s_add_u32 s49, s0, 0x1e000000
	v_lshrrev_b16_e32 v0, 1, v0
	v_bitop3_b32 v1, v1, s4, v4 bitop3:0xde
	v_bitop3_b32 v169, s5, v3, v4 bitop3:0xf6
	s_addc_u32 s60, s1, 0
	v_add_lshl_u32 v152, v10, v0, 1
	v_add_lshl_u32 v154, v11, v0, 1
	s_add_i32 s78, 0, 0x10000
	s_add_i32 s79, 0, 0x14000
	v_mbcnt_lo_u32_b32 v0, -1, 0
	v_mov_b32_e32 v153, v147
	v_mov_b32_e32 v155, v147
	v_mov_b64_e32 v[156:157], 0x300
	v_mov_b64_e32 v[158:159], 0x2ff
	s_movk_i32 s61, 0x61
	v_add_u32_e32 v171, s78, v169
	v_add_u32_e32 v172, s79, v169
	v_add_u32_e32 v173, 0, v1
	v_mbcnt_hi_u32_b32 v174, -1, v0
	s_barrier
	v_bfe_u32 v232, v230, 6, 2
	v_bfe_u32 v231, v230, 2, 4
	v_lshl_add_u32 v231, v232, 4, v231
	v_mul_u32_u24_e32 v231, 0x1600, v231
	v_lshrrev_b32_e32 v232, 8, v230
	v_lshl_add_u32 v231, v232, 7, v231
	v_and_b32_e32 v232, 1, v230
	v_lshl_add_u32 v231, v232, 6, v231
	s_branch .LBB0_259

; #define PG8_STAGE(bufoff, gbase, voff) do { _Pragma("unroll") for (int _i = 0; _i < 2; ++_i) \
;         __builtin_amdgcn_global_load_lds((const unsigned*)((const char*)(gbase) + (voff)[_i]), (PG8_LAS unsigned*)(lds + (bufoff) + ldsw + _i * 8192), 16, 0, 0); } while (0)
; #define PG8_LDA(dst, b, h) do { _Pragma("unroll") for (int m = 0; m < 4; ++m) _Pragma("unroll") for (int k = 0; k < 2; ++k) dst[m][k] = *(const PG8_LAS bf16x8*)(lds + PG8_SA(b, h) + aoff + m * 2048 + k * 1024); } while (0)
; #define PG8_LDB(dst, b, h) do { _Pragma("unroll") for (int n = 0; n < 2; ++n) _Pragma("unroll") for (int k = 0; k < 2; ++k) dst[n][k] = *(const PG8_LAS bf16x8*)(lds + PG8_SB(b, h) + boff + n * 2048 + k * 1024); } while (0)
; #define PG8_MMA(ai, bj, At, Bt) do { __builtin_amdgcn_s_setprio(1); _Pragma("unroll") for (int m = 0; m < 4; ++m) _Pragma("unroll") for (int n = 0; n < 2; ++n) _Pragma("unroll") for (int k = 0; k < 2; ++k) \
;         acc[ai][bj][m][n] = __builtin_amdgcn_mfma_f32_16x16x32_bf16(Bt[n][k], At[m][k], acc[ai][bj][m][n], 0, 0, 0); __builtin_amdgcn_s_setprio(0); } while (0)
; #define PG8_WAIT_V(n) asm volatile("s_waitcnt vmcnt(" #n ")" ::: "memory")
; #define PG8_WAIT_L(n) asm volatile("s_waitcnt lgkmcnt(" #n ")" ::: "memory")
; #define PG8_BAR __builtin_amdgcn_s_barrier()
; #define PG8_SCHED __builtin_amdgcn_sched_barrier(0)
; template <class Epi, class Sched, bool ALIGN_EPI = false, bool SP2 = false>
; __device__ __forceinline__ void gemm_phase(PG8_LAS unsigned char* lds, const Gemm g, const Sched& S, const Epi& E) {
;     ...
;             PG8_LDB(B0, 0, 0); PG8_LDB(B1, 0, 1); PG8_SCHED; PG8_LDA(At, 0, 0); PG8_STAGE(PG8_SA(1, 1), a1 + hstep, voffA);
;             PG8_WAIT_V(8); PG8_WAIT_L(0); PG8_BAR; PG8_MMA(0, 0, At, B0); PG8_MMA(0, 1, At, B1); PG8_BAR; PG8_SCHED;
;             PG8_LDA(At, 0, 1); PG8_STAGE(PG8_SB(0, 0), b2, voffB); PG8_STAGE(PG8_SB(0, 1), b2 + hstep, voffB); PG8_STAGE(PG8_SA(0, 0), a2, voffA);
.LBB0_266:
	ds_read_b128 v[128:131], v171
	ds_read_b128 v[132:135], v171 offset:1024
	ds_read_b128 v[136:139], v171 offset:2048
	ds_read_b128 v[140:143], v171 offset:3072
	ds_read_b128 v[160:163], v172
	ds_read_b128 v[164:167], v172 offset:1024
	ds_read_b128 v[176:179], v172 offset:2048
	ds_read_b128 v[182:185], v172 offset:3072
	s_add_u32 s22, s20, 0xfff50080
	s_addc_u32 s23, s21, -1
	s_cmp_eq_u32 s86, 40
	s_cselect_b32 s25, s1, s23
	s_cselect_b32 s24, s0, s22
	s_cselect_b32 s23, s7, s85
	s_cselect_b32 s22, s6, s84
	v_lshl_add_u64 v[220:221], s[20:21], 0, v[152:153]
	s_add_i32 m0, s40, 0xc000
	ds_read_b128 v[186:189], v173
	ds_read_b128 v[192:195], v173 offset:1024
	ds_read_b128 v[196:199], v173 offset:2048
	ds_read_b128 v[200:203], v173 offset:3072
	ds_read_b128 v[204:207], v173 offset:4096
	ds_read_b128 v[208:211], v173 offset:5120
	ds_read_b128 v[212:215], v173 offset:6144
	ds_read_b128 v[216:219], v173 offset:7168
	global_load_lds_dwordx4 v[220:221], off
	v_lshl_add_u64 v[220:221], s[20:21], 0, v[154:155]
	s_add_i32 m0, s40, 0xe000
	s_nop 0
	global_load_lds_dwordx4 v[220:221], off
	s_add_u32 s100, s20, 0xfff50180
	s_addc_u32 s101, s21, -1
	s_mul_i32 s98, s82, 0x58000
	v_add_u32_e32 v232, s98, v231
	global_load_dword v233, v232, s[100:101]
	s_waitcnt vmcnt(9)
	s_waitcnt lgkmcnt(0)
	s_barrier
	s_setprio 1
	s_waitcnt lgkmcnt(0)
	v_mfma_f32_16x16x32_bf16 v[124:127], v[128:131], v[186:189], v[124:127]
	v_mfma_f32_16x16x32_bf16 v[120:123], v[136:139], v[186:189], v[120:123]
	v_mfma_f32_16x16x32_bf16 v[108:111], v[128:131], v[196:199], v[108:111]
	v_mfma_f32_16x16x32_bf16 v[104:107], v[136:139], v[196:199], v[104:107]
	v_mfma_f32_16x16x32_bf16 v[92:95], v[128:131], v[204:207], v[92:95]
	v_mfma_f32_16x16x32_bf16 v[88:91], v[136:139], v[204:207], v[88:91]
	v_mfma_f32_16x16x32_bf16 v[76:79], v[128:131], v[212:215], v[76:79]
	v_mfma_f32_16x16x32_bf16 v[72:75], v[136:139], v[212:215], v[72:75]
	v_mfma_f32_16x16x32_bf16 v[124:127], v[132:135], v[192:195], v[124:127]
	v_mfma_f32_16x16x32_bf16 v[120:123], v[140:143], v[192:195], v[120:123]
	v_mfma_f32_16x16x32_bf16 v[108:111], v[132:135], v[200:203], v[108:111]
	v_mfma_f32_16x16x32_bf16 v[104:107], v[140:143], v[200:203], v[104:107]
	v_mfma_f32_16x16x32_bf16 v[92:95], v[132:135], v[208:211], v[92:95]
	v_mfma_f32_16x16x32_bf16 v[88:91], v[140:143], v[208:211], v[88:91]
	v_mfma_f32_16x16x32_bf16 v[76:79], v[132:135], v[216:219], v[76:79]
	v_mfma_f32_16x16x32_bf16 v[72:75], v[140:143], v[216:219], v[72:75]
	s_setprio 0
	s_setprio 1
	v_mfma_f32_16x16x32_bf16 v[116:119], v[160:163], v[186:189], v[116:119]
	v_mfma_f32_16x16x32_bf16 v[112:115], v[176:179], v[186:189], v[112:115]
	v_mfma_f32_16x16x32_bf16 v[100:103], v[160:163], v[196:199], v[100:103]
	v_mfma_f32_16x16x32_bf16 v[96:99], v[176:179], v[196:199], v[96:99]
	v_mfma_f32_16x16x32_bf16 v[84:87], v[160:163], v[204:207], v[84:87]
	v_mfma_f32_16x16x32_bf16 v[80:83], v[176:179], v[204:207], v[80:83]
	v_mfma_f32_16x16x32_bf16 v[68:71], v[160:163], v[212:215], v[68:71]
	v_mfma_f32_16x16x32_bf16 v[64:67], v[176:179], v[212:215], v[64:67]
	v_mfma_f32_16x16x32_bf16 v[116:119], v[164:167], v[192:195], v[116:119]
	v_mfma_f32_16x16x32_bf16 v[112:115], v[182:185], v[192:195], v[112:115]
	v_mfma_f32_16x16x32_bf16 v[100:103], v[164:167], v[200:203], v[100:103]
	v_mfma_f32_16x16x32_bf16 v[96:99], v[182:185], v[200:203], v[96:99]
	v_mfma_f32_16x16x32_bf16 v[84:87], v[164:167], v[208:211], v[84:87]
	v_mfma_f32_16x16x32_bf16 v[80:83], v[182:185], v[208:211], v[80:83]
	v_mfma_f32_16x16x32_bf16 v[68:71], v[164:167], v[216:219], v[68:71]
	v_mfma_f32_16x16x32_bf16 v[64:67], v[182:185], v[216:219], v[64:67]
	s_setprio 0
	s_barrier
	s_add_i32 s87, s78, s27
	v_lshl_add_u64 v[220:221], s[22:23], 0, v[146:147]
	s_mov_b32 m0, s87
	ds_read_b128 v[186:189], v173 offset:16384
	ds_read_b128 v[192:195], v173 offset:17408
	ds_read_b128 v[196:199], v173 offset:18432
	ds_read_b128 v[200:203], v173 offset:19456
	ds_read_b128 v[204:207], v173 offset:20480
	ds_read_b128 v[208:211], v173 offset:21504
	ds_read_b128 v[212:215], v173 offset:22528
	ds_read_b128 v[216:219], v173 offset:23552
	global_load_lds_dwordx4 v[220:221], off
	s_add_i32 m0, s87, 0x2000
	s_add_u32 s88, s22, 0xb0000
	v_lshl_add_u64 v[222:223], s[22:23], 0, v[150:151]
	s_addc_u32 s89, s23, 0
	s_add_i32 s87, s79, s27
	global_load_lds_dwordx4 v[222:223], off
	v_lshl_add_u64 v[224:225], s[88:89], 0, v[146:147]
	s_mov_b32 m0, s87
	v_lshl_add_u64 v[226:227], s[24:25], 0, v[148:149]
	global_load_lds_dwordx4 v[224:225], off
	v_lshl_add_u64 v[224:225], s[88:89], 0, v[150:151]
	s_add_i32 m0, s87, 0x2000
	s_nop 0
	global_load_lds_dwordx4 v[224:225], off
	v_lshl_add_u64 v[224:225], s[24:25], 0, v[144:145]
	s_mov_b32 m0, s40
	s_nop 0
	global_load_lds_dwordx4 v[224:225], off
	s_mov_b32 m0, s41
	s_nop 0
	global_load_lds_dwordx4 v[226:227], off
	s_waitcnt vmcnt(9)
	s_waitcnt lgkmcnt(0)
	s_barrier
; #define PG8_STAGE(bufoff, gbase, voff) do { _Pragma("unroll") for (int _i = 0; _i < 2; ++_i) \
;         __builtin_amdgcn_global_load_lds((const unsigned*)((const char*)(gbase) + (voff)[_i]), (PG8_LAS unsigned*)(lds + (bufoff) + ldsw + _i * 8192), 16, 0, 0); } while (0)
; #define PG8_LDA(dst, b, h) do { _Pragma("unroll") for (int m = 0; m < 4; ++m) _Pragma("unroll") for (int k = 0; k < 2; ++k) dst[m][k] = *(const PG8_LAS bf16x8*)(lds + PG8_SA(b, h) + aoff + m * 2048 + k * 1024); } while (0)
; #define PG8_LDB(dst, b, h) do { _Pragma("unroll") for (int n = 0; n < 2; ++n) _Pragma("unroll") for (int k = 0; k < 2; ++k) dst[n][k] = *(const PG8_LAS bf16x8*)(lds + PG8_SB(b, h) + boff + n * 2048 + k * 1024); } while (0)
; #define PG8_MMA(ai, bj, At, Bt) do { __builtin_amdgcn_s_setprio(1); _Pragma("unroll") for (int m = 0; m < 4; ++m) _Pragma("unroll") for (int n = 0; n < 2; ++n) _Pragma("unroll") for (int k = 0; k < 2; ++k) \
;         acc[ai][bj][m][n] = __builtin_amdgcn_mfma_f32_16x16x32_bf16(Bt[n][k], At[m][k], acc[ai][bj][m][n], 0, 0, 0); __builtin_amdgcn_s_setprio(0); } while (0)
; #define PG8_WAIT_V(n) asm volatile("s_waitcnt vmcnt(" #n ")" ::: "memory")
; #define PG8_WAIT_L(n) asm volatile("s_waitcnt lgkmcnt(" #n ")" ::: "memory")
; #define PG8_BAR __builtin_amdgcn_s_barrier()
; #define PG8_SCHED __builtin_amdgcn_sched_barrier(0)
; template <class Epi, class Sched, bool ALIGN_EPI = false, bool SP2 = false>
; __device__ __forceinline__ void gemm_phase(PG8_LAS unsigned char* lds, const Gemm g, const Sched& S, const Epi& E) {
;     ...
;             PG8_WAIT_V(8); PG8_WAIT_L(0); PG8_BAR; PG8_MMA(1, 0, At, B0); PG8_MMA(1, 1, At, B1); PG8_BAR; PG8_SCHED;
;             PG8_LDB(B0, 1, 0); PG8_LDB(B1, 1, 1); PG8_SCHED; PG8_LDA(At, 1, 0); PG8_STAGE(PG8_SA(0, 1), a2 + hstep, voffA);
;             PG8_WAIT_V(8); PG8_WAIT_L(0); PG8_BAR; PG8_MMA(0, 0, At, B0); PG8_MMA(0, 1, At, B1); PG8_BAR; PG8_SCHED;
	s_setprio 1
	s_waitcnt lgkmcnt(0)
	v_mfma_f32_16x16x32_bf16 v[60:63], v[128:131], v[186:189], v[60:63]
	v_mfma_f32_16x16x32_bf16 v[56:59], v[136:139], v[186:189], v[56:59]
	v_mfma_f32_16x16x32_bf16 v[44:47], v[128:131], v[196:199], v[44:47]
	v_mfma_f32_16x16x32_bf16 v[40:43], v[136:139], v[196:199], v[40:43]
	v_mfma_f32_16x16x32_bf16 v[28:31], v[128:131], v[204:207], v[28:31]
	v_mfma_f32_16x16x32_bf16 v[24:27], v[136:139], v[204:207], v[24:27]
	v_mfma_f32_16x16x32_bf16 v[12:15], v[128:131], v[212:215], v[12:15]
	v_mfma_f32_16x16x32_bf16 v[8:11], v[136:139], v[212:215], v[8:11]
	v_mfma_f32_16x16x32_bf16 v[60:63], v[132:135], v[192:195], v[60:63]
	v_mfma_f32_16x16x32_bf16 v[56:59], v[140:143], v[192:195], v[56:59]
	v_mfma_f32_16x16x32_bf16 v[44:47], v[132:135], v[200:203], v[44:47]
	v_mfma_f32_16x16x32_bf16 v[40:43], v[140:143], v[200:203], v[40:43]
	v_mfma_f32_16x16x32_bf16 v[28:31], v[132:135], v[208:211], v[28:31]
	v_mfma_f32_16x16x32_bf16 v[24:27], v[140:143], v[208:211], v[24:27]
	v_mfma_f32_16x16x32_bf16 v[12:15], v[132:135], v[216:219], v[12:15]
	v_mfma_f32_16x16x32_bf16 v[8:11], v[140:143], v[216:219], v[8:11]
	s_setprio 0
	s_setprio 1
	v_mfma_f32_16x16x32_bf16 v[52:55], v[160:163], v[186:189], v[52:55]
	v_mfma_f32_16x16x32_bf16 v[48:51], v[176:179], v[186:189], v[48:51]
	v_mfma_f32_16x16x32_bf16 v[36:39], v[160:163], v[196:199], v[36:39]
	v_mfma_f32_16x16x32_bf16 v[32:35], v[176:179], v[196:199], v[32:35]
	v_mfma_f32_16x16x32_bf16 v[20:23], v[160:163], v[204:207], v[20:23]
	v_mfma_f32_16x16x32_bf16 v[16:19], v[176:179], v[204:207], v[16:19]
	v_mfma_f32_16x16x32_bf16 v[4:7], v[160:163], v[212:215], v[4:7]
	v_mfma_f32_16x16x32_bf16 v[0:3], v[176:179], v[212:215], v[0:3]
	v_mfma_f32_16x16x32_bf16 v[52:55], v[164:167], v[192:195], v[52:55]
	v_mfma_f32_16x16x32_bf16 v[48:51], v[182:185], v[192:195], v[48:51]
	v_mfma_f32_16x16x32_bf16 v[36:39], v[164:167], v[200:203], v[36:39]
	v_mfma_f32_16x16x32_bf16 v[32:35], v[182:185], v[200:203], v[32:35]
	v_mfma_f32_16x16x32_bf16 v[20:23], v[164:167], v[208:211], v[20:23]
	v_mfma_f32_16x16x32_bf16 v[16:19], v[182:185], v[208:211], v[16:19]
	v_mfma_f32_16x16x32_bf16 v[4:7], v[164:167], v[216:219], v[4:7]
	v_mfma_f32_16x16x32_bf16 v[0:3], v[182:185], v[216:219], v[0:3]
	s_setprio 0
	s_barrier
	s_add_i32 s87, 0, 0x18000
	s_add_i32 s88, 0, 0x1c000
	v_add_u32_e32 v140, s87, v169
	v_add_u32_e32 v175, s88, v169
	ds_read_b128 v[128:131], v140
	ds_read_b128 v[132:135], v140 offset:1024
	ds_read_b128 v[136:139], v140 offset:2048
	ds_read_b128 v[140:143], v140 offset:3072
	ds_read_b128 v[160:163], v175
	ds_read_b128 v[164:167], v175 offset:1024
	ds_read_b128 v[176:179], v175 offset:2048
	ds_read_b128 v[182:185], v175 offset:3072
	s_add_u32 s24, s24, 0xb0000
	s_addc_u32 s25, s25, 0
	s_mov_b32 m0, s42
	v_lshl_add_u64 v[228:229], s[24:25], 0, v[144:145]
	ds_read_b128 v[186:189], v173 offset:32768
	ds_read_b128 v[192:195], v173 offset:33792
	ds_read_b128 v[196:199], v173 offset:34816
	ds_read_b128 v[200:203], v173 offset:35840
	ds_read_b128 v[204:207], v173 offset:36864
	ds_read_b128 v[208:211], v173 offset:37888
	ds_read_b128 v[212:215], v173 offset:38912
	ds_read_b128 v[216:219], v173 offset:39936
	global_load_lds_dwordx4 v[228:229], off
	v_lshl_add_u64 v[228:229], s[24:25], 0, v[148:149]
	s_mov_b32 m0, s43
	s_nop 0
	global_load_lds_dwordx4 v[228:229], off
	s_waitcnt vmcnt(9)
	s_waitcnt lgkmcnt(0)
	s_barrier
	s_setprio 1
	s_waitcnt lgkmcnt(0)
	v_mfma_f32_16x16x32_bf16 v[124:127], v[128:131], v[186:189], v[124:127]
	v_mfma_f32_16x16x32_bf16 v[120:123], v[136:139], v[186:189], v[120:123]
	v_mfma_f32_16x16x32_bf16 v[108:111], v[128:131], v[196:199], v[108:111]
	v_mfma_f32_16x16x32_bf16 v[104:107], v[136:139], v[196:199], v[104:107]
	v_mfma_f32_16x16x32_bf16 v[92:95], v[128:131], v[204:207], v[92:95]
	v_mfma_f32_16x16x32_bf16 v[88:91], v[136:139], v[204:207], v[88:91]
	v_mfma_f32_16x16x32_bf16 v[76:79], v[128:131], v[212:215], v[76:79]
	v_mfma_f32_16x16x32_bf16 v[72:75], v[136:139], v[212:215], v[72:75]
	v_mfma_f32_16x16x32_bf16 v[124:127], v[132:135], v[192:195], v[124:127]
	v_mfma_f32_16x16x32_bf16 v[120:123], v[140:143], v[192:195], v[120:123]
	v_mfma_f32_16x16x32_bf16 v[108:111], v[132:135], v[200:203], v[108:111]
	v_mfma_f32_16x16x32_bf16 v[104:107], v[140:143], v[200:203], v[104:107]
	v_mfma_f32_16x16x32_bf16 v[92:95], v[132:135], v[208:211], v[92:95]
	v_mfma_f32_16x16x32_bf16 v[88:91], v[140:143], v[208:211], v[88:91]
	v_mfma_f32_16x16x32_bf16 v[76:79], v[132:135], v[216:219], v[76:79]
	v_mfma_f32_16x16x32_bf16 v[72:75], v[140:143], v[216:219], v[72:75]
	s_setprio 0
	s_setprio 1
	v_mfma_f32_16x16x32_bf16 v[116:119], v[160:163], v[186:189], v[116:119]
	v_mfma_f32_16x16x32_bf16 v[112:115], v[176:179], v[186:189], v[112:115]
	v_mfma_f32_16x16x32_bf16 v[100:103], v[160:163], v[196:199], v[100:103]
	v_mfma_f32_16x16x32_bf16 v[96:99], v[176:179], v[196:199], v[96:99]
	v_mfma_f32_16x16x32_bf16 v[84:87], v[160:163], v[204:207], v[84:87]
	v_mfma_f32_16x16x32_bf16 v[80:83], v[176:179], v[204:207], v[80:83]
	v_mfma_f32_16x16x32_bf16 v[68:71], v[160:163], v[212:215], v[68:71]
	v_mfma_f32_16x16x32_bf16 v[64:67], v[176:179], v[212:215], v[64:67]
	v_mfma_f32_16x16x32_bf16 v[116:119], v[164:167], v[192:195], v[116:119]
	v_mfma_f32_16x16x32_bf16 v[112:115], v[182:185], v[192:195], v[112:115]
	v_mfma_f32_16x16x32_bf16 v[100:103], v[164:167], v[200:203], v[100:103]
	v_mfma_f32_16x16x32_bf16 v[96:99], v[182:185], v[200:203], v[96:99]
	v_mfma_f32_16x16x32_bf16 v[84:87], v[164:167], v[208:211], v[84:87]
	v_mfma_f32_16x16x32_bf16 v[80:83], v[182:185], v[208:211], v[80:83]
	v_mfma_f32_16x16x32_bf16 v[68:71], v[164:167], v[216:219], v[68:71]
	v_mfma_f32_16x16x32_bf16 v[64:67], v[182:185], v[216:219], v[64:67]
	s_setprio 0
	s_barrier
; #define PG8_STAGE(bufoff, gbase, voff) do { _Pragma("unroll") for (int _i = 0; _i < 2; ++_i) \
;         __builtin_amdgcn_global_load_lds((const unsigned*)((const char*)(gbase) + (voff)[_i]), (PG8_LAS unsigned*)(lds + (bufoff) + ldsw + _i * 8192), 16, 0, 0); } while (0)
; #define PG8_LDA(dst, b, h) do { _Pragma("unroll") for (int m = 0; m < 4; ++m) _Pragma("unroll") for (int k = 0; k < 2; ++k) dst[m][k] = *(const PG8_LAS bf16x8*)(lds + PG8_SA(b, h) + aoff + m * 2048 + k * 1024); } while (0)
; #define PG8_MMA(ai, bj, At, Bt) do { __builtin_amdgcn_s_setprio(1); _Pragma("unroll") for (int m = 0; m < 4; ++m) _Pragma("unroll") for (int n = 0; n < 2; ++n) _Pragma("unroll") for (int k = 0; k < 2; ++k) \
;         acc[ai][bj][m][n] = __builtin_amdgcn_mfma_f32_16x16x32_bf16(Bt[n][k], At[m][k], acc[ai][bj][m][n], 0, 0, 0); __builtin_amdgcn_s_setprio(0); } while (0)
; #define PG8_WAIT_V(n) asm volatile("s_waitcnt vmcnt(" #n ")" ::: "memory")
; #define PG8_WAIT_L(n) asm volatile("s_waitcnt lgkmcnt(" #n ")" ::: "memory")
; #define PG8_BAR __builtin_amdgcn_s_barrier()
; #define PG8_SCHED __builtin_amdgcn_sched_barrier(0)
; template <class Epi, class Sched, bool ALIGN_EPI = false, bool SP2 = false>
; __device__ __forceinline__ void gemm_phase(PG8_LAS unsigned char* lds, const Gemm g, const Sched& S, const Epi& E) {
;     ...
;             PG8_LDA(At, 1, 1); PG8_STAGE(PG8_SB(1, 0), b3, voffB); PG8_STAGE(PG8_SB(1, 1), b3 + hstep, voffB); PG8_STAGE(PG8_SA(1, 0), a3, voffA);
;             PG8_WAIT_V(8); PG8_WAIT_L(0); PG8_BAR; PG8_MMA(1, 0, At, B0); PG8_MMA(1, 1, At, B1); PG8_BAR; PG8_SCHED;
	s_add_i32 s24, s87, s27
	v_lshl_add_u64 v[220:221], v[220:221], 0, s[18:19]
	s_mov_b32 m0, s24
	ds_read_b128 v[186:189], v173 offset:49152
	ds_read_b128 v[192:195], v173 offset:50176
	ds_read_b128 v[196:199], v173 offset:51200
	ds_read_b128 v[200:203], v173 offset:52224
	ds_read_b128 v[204:207], v173 offset:53248
	ds_read_b128 v[208:211], v173 offset:54272
	ds_read_b128 v[212:215], v173 offset:55296
	ds_read_b128 v[216:219], v173 offset:56320
	global_load_lds_dwordx4 v[220:221], off
	s_add_i32 m0, s24, 0x2000
	s_add_u32 s22, s22, 0xb0080
	v_lshl_add_u64 v[220:221], v[222:223], 0, s[18:19]
	s_addc_u32 s23, s23, 0
	s_add_i32 s24, s88, s27
	global_load_lds_dwordx4 v[220:221], off
	v_lshl_add_u64 v[220:221], s[22:23], 0, v[146:147]
	s_mov_b32 m0, s24
	s_nop 0
	global_load_lds_dwordx4 v[220:221], off
	v_lshl_add_u64 v[220:221], s[22:23], 0, v[150:151]
	s_add_i32 m0, s24, 0x2000
	s_nop 0
	global_load_lds_dwordx4 v[220:221], off
	v_lshl_add_u64 v[220:221], v[224:225], 0, s[18:19]
	s_mov_b32 m0, s45
	s_nop 0
	global_load_lds_dwordx4 v[220:221], off
	v_lshl_add_u64 v[220:221], v[226:227], 0, s[18:19]
	s_mov_b32 m0, s46
	s_nop 0
	global_load_lds_dwordx4 v[220:221], off
	s_waitcnt vmcnt(8)
	s_waitcnt lgkmcnt(0)
	s_barrier
	s_setprio 1
	s_waitcnt lgkmcnt(0)
	v_mfma_f32_16x16x32_bf16 v[60:63], v[128:131], v[186:189], v[60:63]
	v_mfma_f32_16x16x32_bf16 v[56:59], v[136:139], v[186:189], v[56:59]
	v_mfma_f32_16x16x32_bf16 v[44:47], v[128:131], v[196:199], v[44:47]
	v_mfma_f32_16x16x32_bf16 v[40:43], v[136:139], v[196:199], v[40:43]
	v_mfma_f32_16x16x32_bf16 v[28:31], v[128:131], v[204:207], v[28:31]
	v_mfma_f32_16x16x32_bf16 v[24:27], v[136:139], v[204:207], v[24:27]
	v_mfma_f32_16x16x32_bf16 v[12:15], v[128:131], v[212:215], v[12:15]
	v_mfma_f32_16x16x32_bf16 v[8:11], v[136:139], v[212:215], v[8:11]
	v_mfma_f32_16x16x32_bf16 v[60:63], v[132:135], v[192:195], v[60:63]
	v_mfma_f32_16x16x32_bf16 v[56:59], v[140:143], v[192:195], v[56:59]
	v_mfma_f32_16x16x32_bf16 v[44:47], v[132:135], v[200:203], v[44:47]
	v_mfma_f32_16x16x32_bf16 v[40:43], v[140:143], v[200:203], v[40:43]
	v_mfma_f32_16x16x32_bf16 v[28:31], v[132:135], v[208:211], v[28:31]
	v_mfma_f32_16x16x32_bf16 v[24:27], v[140:143], v[208:211], v[24:27]
	v_mfma_f32_16x16x32_bf16 v[12:15], v[132:135], v[216:219], v[12:15]
	v_mfma_f32_16x16x32_bf16 v[8:11], v[140:143], v[216:219], v[8:11]
	s_setprio 0
	s_setprio 1
	v_mfma_f32_16x16x32_bf16 v[52:55], v[160:163], v[186:189], v[52:55]
	v_mfma_f32_16x16x32_bf16 v[48:51], v[176:179], v[186:189], v[48:51]
	v_mfma_f32_16x16x32_bf16 v[36:39], v[160:163], v[196:199], v[36:39]
	v_mfma_f32_16x16x32_bf16 v[32:35], v[176:179], v[196:199], v[32:35]
	v_mfma_f32_16x16x32_bf16 v[20:23], v[160:163], v[204:207], v[20:23]
	v_mfma_f32_16x16x32_bf16 v[16:19], v[176:179], v[204:207], v[16:19]
	v_mfma_f32_16x16x32_bf16 v[4:7], v[160:163], v[212:215], v[4:7]
	v_mfma_f32_16x16x32_bf16 v[0:3], v[176:179], v[212:215], v[0:3]
	v_mfma_f32_16x16x32_bf16 v[52:55], v[164:167], v[192:195], v[52:55]
	v_mfma_f32_16x16x32_bf16 v[48:51], v[182:185], v[192:195], v[48:51]
	v_mfma_f32_16x16x32_bf16 v[36:39], v[164:167], v[200:203], v[36:39]
	v_mfma_f32_16x16x32_bf16 v[32:35], v[182:185], v[200:203], v[32:35]
	v_mfma_f32_16x16x32_bf16 v[20:23], v[164:167], v[208:211], v[20:23]
	v_mfma_f32_16x16x32_bf16 v[16:19], v[182:185], v[208:211], v[16:19]
	v_mfma_f32_16x16x32_bf16 v[4:7], v[164:167], v[216:219], v[4:7]
	v_mfma_f32_16x16x32_bf16 v[0:3], v[182:185], v[216:219], v[0:3]
	s_setprio 0
	s_barrier
	s_add_i32 s86, s86, 2
	s_add_u32 s20, s20, 0x100
	s_addc_u32 s21, s21, 0
	s_add_u32 s84, s84, 0x100
	s_addc_u32 s85, s85, 0
	s_cmp_gt_u32 s86, 41
	s_cbranch_scc0 .LBB0_266
; __device__ __forceinline__ u32x2 pack4(f32x4 v) { u32x2 w; w.x = cvt_pk_bf16(v[0], v[1]); w.y = cvt_pk_bf16(v[2], v[3]); return w; }
;     __device__ __forceinline__ void operator()(const f32x4 (&acc)[2][2][4][2], const Unit& u, int wr, int wc, int fr, int fq) const {
;         const int row0 = u.pm * BM + wr * 64 + fr, col0 = u.pn * BM + wc * 32 + 8 * fq;
;         const float* base = (u.pm * BM < split) ? base0 : base1; bf16_t* const xn = (bf16_t*)(ws + WS_XN); float* const ssq = (float*)(ws + WS_SSQ);
; #pragma unroll
;         for (int ai = 0; ai < 2; ++ai)
; #pragma unroll
;         for (int mh = 0; mh < 4; mh += 2) {
;             f32x4 pre[4][2][2];
; #pragma unroll
;             for (int m = mh; m < mh + 2; ++m)
; #pragma unroll
;                 for (int bj = 0; bj < 2; ++bj)
; #pragma unroll
;                     for (int n = 0; n < 2; ++n) pre[m][bj][n] = *(const f32x4*)(base + (size_t)(row0 + ai * HALF + m * 16) * 1024 + col0 + bj * HALF + n * 4);
;             asm volatile("" ::: "memory");
; #pragma unroll
;             for (int m = mh; m < mh + 2; ++m) { const int row = row0 + ai * HALF + m * 16; const size_t off = (size_t)row * 1024 + col0; float ss = 0.f;
; #pragma unroll
;                 for (int bj = 0; bj < 2; ++bj) { u32x4e w;
; #pragma unroll
;                     for (int n = 0; n < 2; ++n) { const f32x4 o = pre[m][bj][n] + acc[ai][bj][m][n] * s;
;                         *(f32x4*)(out + off + bj * HALF + n * 4) = o;
;                         if (NORMOUT) { const u32x2 p = pack4(o); w[2 * n] = p.x; w[2 * n + 1] = p.y; ss += (o[0] * o[0] + o[1] * o[1]) + (o[2] * o[2] + o[3] * o[3]); } }
;                     if (NORMOUT) *(u32x4e*)(xn + off + bj * HALF) = w; }
;                 if (NORMOUT) { ss += __shfl_xor(ss, 16); ss += __shfl_xor(ss, 32); if (fq == 0) ssq[(size_t)row * 16 + u.pn * 4 + wc] = ss; } }
	s_cmpk_lt_i32 s83, 0x80
	v_lshl_add_u32 v162, s83, 8, v168
	v_lshl_or_b32 v160, s82, 8, v170
	s_cselect_b32 s20, s37, s39
	s_cselect_b32 s21, s36, s38
	v_mov_b32_e32 v128, s21
	v_mov_b32_e32 v129, s20
	v_ashrrev_i32_e32 v161, 31, v160
	v_ashrrev_i32_e32 v163, 31, v162
	v_lshl_add_u64 v[164:165], v[160:161], 2, v[128:129]
	v_lshlrev_b64 v[128:129], 12, v[162:163]
	v_lshl_add_u64 v[128:129], v[164:165], 0, v[128:129]
	global_load_dwordx4 v[182:185], v[128:129], off
	global_load_dwordx4 v[186:189], v[128:129], off offset:16
	global_load_dwordx4 v[192:195], v[128:129], off offset:512
	global_load_dwordx4 v[196:199], v[128:129], off offset:528
	v_or_b32_e32 v166, 16, v162
	v_ashrrev_i32_e32 v167, 31, v166
	v_lshlrev_b64 v[128:129], 12, v[166:167]
	v_lshl_add_u64 v[132:133], v[164:165], 0, v[128:129]
	global_load_dwordx4 v[136:139], v[132:133], off offset:16
	global_load_dwordx4 v[140:143], v[132:133], off
	global_load_dwordx4 v[128:131], v[132:133], off offset:528
	s_nop 0
	global_load_dwordx4 v[132:135], v[132:133], off offset:512
	v_and_b32_e32 v176, 64, v174
	v_xor_b32_e32 v175, 16, v174
	v_add_u32_e32 v176, 64, v176
	v_lshlrev_b64 v[178:179], 10, v[162:163]
	v_xor_b32_e32 v177, 32, v174
	v_cmp_lt_i32_e32 vcc, v175, v176
	v_lshl_add_u64 v[178:179], v[178:179], 0, v[160:161]
	v_lshl_add_u64 v[200:201], v[178:179], 1, s[64:65]
	v_cndmask_b32_e32 v175, v174, v175, vcc
	v_cmp_lt_i32_e32 vcc, v177, v176
	v_lshl_add_u64 v[178:179], v[178:179], 2, s[56:57]
	v_lshlrev_b32_e32 v176, 2, v175
	v_cndmask_b32_e32 v177, v174, v177, vcc
	v_lshlrev_b32_e32 v175, 2, v177
	s_lshl_b32 s20, s82, 2
	s_ashr_i32 s21, s20, 31
	s_lshl_b64 s[20:21], s[20:21], 2
	s_add_u32 s20, s49, s20
	s_addc_u32 s21, s60, s21
	s_waitcnt vmcnt(0)
	v_pk_fma_f32 v[126:127], v[126:127], 0.5, v[184:185] op_sel_hi:[1,0,1]
	v_pk_fma_f32 v[124:125], v[124:125], 0.5, v[182:183] op_sel_hi:[1,0,1]
	v_pk_fma_f32 v[122:123], v[122:123], 0.5, v[188:189] op_sel_hi:[1,0,1]
	v_pk_fma_f32 v[120:121], v[120:121], 0.5, v[186:187] op_sel_hi:[1,0,1]
	v_pk_fma_f32 v[118:119], v[118:119], 0.5, v[194:195] op_sel_hi:[1,0,1]
	v_pk_fma_f32 v[116:117], v[116:117], 0.5, v[192:193] op_sel_hi:[1,0,1]
	v_pk_fma_f32 v[184:185], v[114:115], 0.5, v[198:199] op_sel_hi:[1,0,1]
	v_pk_fma_f32 v[182:183], v[112:113], 0.5, v[196:197] op_sel_hi:[1,0,1]
	global_store_dwordx4 v[178:179], v[124:127], off
	v_cvt_pk_bf16_f32 v112, v124, v125
	v_cvt_pk_bf16_f32 v113, v126, v127
	v_mul_f32_e32 v125, v125, v125
	v_mul_f32_e32 v127, v127, v127
	global_store_dwordx4 v[178:179], v[120:123], off offset:16
	v_cvt_pk_bf16_f32 v114, v120, v121
	v_cvt_pk_bf16_f32 v115, v122, v123
	v_mul_f32_e32 v121, v121, v121
	v_mul_f32_e32 v123, v123, v123
	v_mul_f32_e32 v177, v117, v117
	v_mul_f32_e32 v181, v119, v119
	v_fmac_f32_e32 v125, v124, v124
	v_fmac_f32_e32 v127, v126, v126
	v_fmac_f32_e32 v121, v120, v120
	v_fmac_f32_e32 v123, v122, v122
	v_mul_f32_e32 v186, v183, v183
	v_mul_f32_e32 v187, v185, v185
	v_fmac_f32_e32 v177, v116, v116
	v_fmac_f32_e32 v181, v118, v118
	v_add_f32_e32 v120, v125, v127
	v_add_f32_e32 v121, v121, v123
	v_fmac_f32_e32 v186, v182, v182
	v_fmac_f32_e32 v187, v184, v184
	v_add_f32_e32 v122, v177, v181
	v_add_f32_e32 v120, v120, v121
	v_add_f32_e32 v120, v122, v120
	v_add_f32_e32 v121, v186, v187
	v_add_f32_e32 v120, v121, v120
	ds_bpermute_b32 v121, v176, v120
	global_store_dwordx4 v[200:201], v[112:115], off
	global_store_dwordx4 v[178:179], v[116:119], off offset:512
	global_store_dwordx4 v[178:179], v[182:185], off offset:528
	v_cvt_pk_bf16_f32 v114, v116, v117
	v_cvt_pk_bf16_f32 v115, v118, v119
	s_waitcnt lgkmcnt(0)
	v_add_f32_e32 v112, v120, v121
	ds_bpermute_b32 v113, v175, v112
	v_cvt_pk_bf16_f32 v116, v182, v183
	v_cvt_pk_bf16_f32 v117, v184, v185
	global_store_dwordx4 v[200:201], v[114:117], off offset:256
	s_and_saveexec_b64 s[22:23], s[2:3]
	s_cbranch_execz .LBB0_269
	v_lshlrev_b64 v[114:115], 6, v[162:163]
	v_lshl_add_u64 v[114:115], s[20:21], 0, v[114:115]
	s_waitcnt lgkmcnt(0)
	v_add_f32_e32 v112, v112, v113
	global_store_dword v[114:115], v112, off

; __global__ void __launch_bounds__(NWAVES * 64, 2) mega_fwd(Args args) {
	.amdhsa_kernel _Z8mega_fwd4Args
		.amdhsa_group_segment_fixed_size 0
		.amdhsa_private_segment_fixed_size 0
		.amdhsa_kernarg_size 424
		.amdhsa_user_sgpr_count 2
		.amdhsa_user_sgpr_dispatch_ptr 0
		.amdhsa_user_sgpr_queue_ptr 0
		.amdhsa_user_sgpr_kernarg_segment_ptr 1
		.amdhsa_user_sgpr_dispatch_id 0
		.amdhsa_user_sgpr_kernarg_preload_length 0
		.amdhsa_user_sgpr_kernarg_preload_offset 0
		.amdhsa_user_sgpr_private_segment_size 0
		.amdhsa_uses_dynamic_stack 0
		.amdhsa_enable_private_segment 0
		.amdhsa_system_sgpr_workgroup_id_x 1
		.amdhsa_system_sgpr_workgroup_id_y 0
		.amdhsa_system_sgpr_workgroup_id_z 0
		.amdhsa_system_sgpr_workgroup_info 0
		.amdhsa_system_vgpr_workitem_id 2
		.amdhsa_next_free_vgpr 256
		.amdhsa_next_free_sgpr 102
		.amdhsa_accum_offset 256
		.amdhsa_reserve_vcc 1
		.amdhsa_float_round_mode_32 0
		.amdhsa_float_round_mode_16_64 0
		.amdhsa_float_denorm_mode_32 3
		.amdhsa_float_denorm_mode_16_64 3
		.amdhsa_dx10_clamp 1
		.amdhsa_ieee_mode 1
		.amdhsa_fp16_overflow 0
		.amdhsa_tg_split 0
		.amdhsa_exception_fp_ieee_invalid_op 0
		.amdhsa_exception_fp_denorm_src 0
		.amdhsa_exception_fp_ieee_div_zero 0
		.amdhsa_exception_fp_ieee_overflow 0
		.amdhsa_exception_fp_ieee_underflow 0
		.amdhsa_exception_fp_ieee_inexact 0
		.amdhsa_exception_int_div_zero 0
	.end_amdhsa_kernel
